# P12 on top: attention QK K-fragment LDS reads issued up front with counted lgkmcnt waits, V reads behind each QK MFMA
# speedup vs baseline: 1.0046x; 1.0046x over previous
.LBB0_603:
	s_andn2_b64 vcc, exec, s[38:39]
	s_cbranch_vccnz .LBB0_600
	v_or_b32_e32 v0, s91, v190
	v_mad_u32_u24 v0, v0, s78, v216
	ds_read_b128 v[174:177], v0
	ds_read_b128 v[162:165], v0 offset:32
	ds_read_b128 v[158:161], v0 offset:64
	ds_read_b128 v[170:173], v0 offset:96
	ds_read_b128 v[166:169], v0 offset:128
	ds_read_b128 v[154:157], v0 offset:160
	ds_read_b128 v[150:153], v0 offset:192
	ds_read_b128 v[146:149], v0 offset:224
	s_mov_b64 s[38:39], -1
	s_and_b64 vcc, exec, s[30:31]
	v_lshl_add_u32 v182, s90, 6, v217
	v_add_u32_e32 v183, 0x5000, v182
	v_add_u32_e32 v184, 0x6000, v182
	v_add_u32_e32 v185, 0x7000, v182
	v_add_u32_e32 v182, 0x4000, v182
	s_waitcnt lgkmcnt(7)
	v_mfma_f32_32x32x16_bf16 v[66:81], v[174:177], v[82:85], 0
	ds_read2_b64 v[174:177], v182 offset0:128 offset1:130
	s_waitcnt lgkmcnt(7)
	v_mfma_f32_32x32x16_bf16 v[66:81], v[162:165], v[86:89], v[66:81]
	ds_read2_b64 v[162:165], v182 offset0:132 offset1:134
	s_waitcnt lgkmcnt(7)
	v_mfma_f32_32x32x16_bf16 v[66:81], v[158:161], v[90:93], v[66:81]
	ds_read2_b64 v[158:161], v183 offset0:160 offset1:162
	s_waitcnt lgkmcnt(7)
	v_mfma_f32_32x32x16_bf16 v[66:81], v[170:173], v[94:97], v[66:81]
	ds_read2_b64 v[170:173], v183 offset0:164 offset1:166
	s_waitcnt lgkmcnt(7)
	v_mfma_f32_32x32x16_bf16 v[66:81], v[166:169], v[98:101], v[66:81]
	ds_read2_b64 v[166:169], v184 offset0:192 offset1:194
	s_waitcnt lgkmcnt(7)
	v_mfma_f32_32x32x16_bf16 v[66:81], v[154:157], v[102:105], v[66:81]
	ds_read2_b64 v[154:157], v184 offset0:196 offset1:198
	s_waitcnt lgkmcnt(7)
	v_mfma_f32_32x32x16_bf16 v[66:81], v[150:153], v[106:109], v[66:81]
	ds_read2_b64 v[150:153], v185 offset0:224 offset1:226
	s_waitcnt lgkmcnt(7)
	v_mfma_f32_32x32x16_bf16 v[66:81], v[146:149], v[110:113], v[66:81]
	ds_read2_b64 v[146:149], v185 offset0:228 offset1:230
	s_cbranch_vccnz .LBB0_606
	s_nop 10
	v_max_f32_e32 v0, v66, v66
	v_max_f32_e32 v0, 0xff61b1e6, v0
	v_max3_f32 v0, v0, v67, v68
	v_max3_f32 v0, v0, v69, v70
	v_max3_f32 v0, v0, v71, v72
	v_max3_f32 v0, v0, v73, v74
	v_max3_f32 v0, v0, v75, v76
	v_max3_f32 v0, v0, v77, v78
	v_max3_f32 v0, v0, v79, v80
	s_mov_b64 s[38:39], 0

.LBB0_625:
	s_andn2_b64 vcc, exec, s[38:39]
	s_cbranch_vccnz .LBB0_622
	v_or_b32_e32 v0, s91, v190
	v_mad_u32_u24 v0, v0, s78, v216
	ds_read_b128 v[174:177], v0 offset:34816
	ds_read_b128 v[162:165], v0 offset:34848
	ds_read_b128 v[158:161], v0 offset:34880
	ds_read_b128 v[170:173], v0 offset:34912
	ds_read_b128 v[166:169], v0 offset:34944
	ds_read_b128 v[154:157], v0 offset:34976
	ds_read_b128 v[150:153], v0 offset:35008
	ds_read_b128 v[146:149], v0 offset:35040
	s_mov_b64 s[38:39], -1
	s_and_b64 vcc, exec, s[30:31]
	v_lshl_add_u32 v182, s90, 6, v217
	v_add_u32_e32 v183, 0xd800, v182
	v_add_u32_e32 v184, 0xe800, v182
	v_add_u32_e32 v185, 0xf800, v182
	v_add_u32_e32 v182, 0xc800, v182
	s_waitcnt lgkmcnt(7)
	v_mfma_f32_32x32x16_bf16 v[66:81], v[174:177], v[82:85], 0
	ds_read2_b64 v[174:177], v182 offset0:128 offset1:130
	s_waitcnt lgkmcnt(7)
	v_mfma_f32_32x32x16_bf16 v[66:81], v[162:165], v[86:89], v[66:81]
	ds_read2_b64 v[162:165], v182 offset0:132 offset1:134
	s_waitcnt lgkmcnt(7)
	v_mfma_f32_32x32x16_bf16 v[66:81], v[158:161], v[90:93], v[66:81]
	ds_read2_b64 v[158:161], v183 offset0:160 offset1:162
	s_waitcnt lgkmcnt(7)
	v_mfma_f32_32x32x16_bf16 v[66:81], v[170:173], v[94:97], v[66:81]
	ds_read2_b64 v[170:173], v183 offset0:164 offset1:166
	s_waitcnt lgkmcnt(7)
	v_mfma_f32_32x32x16_bf16 v[66:81], v[166:169], v[98:101], v[66:81]
	ds_read2_b64 v[166:169], v184 offset0:192 offset1:194
	s_waitcnt lgkmcnt(7)
	v_mfma_f32_32x32x16_bf16 v[66:81], v[154:157], v[102:105], v[66:81]
	ds_read2_b64 v[154:157], v184 offset0:196 offset1:198
	s_waitcnt lgkmcnt(7)
	v_mfma_f32_32x32x16_bf16 v[66:81], v[150:153], v[106:109], v[66:81]
	ds_read2_b64 v[150:153], v185 offset0:224 offset1:226
	s_waitcnt lgkmcnt(7)
	v_mfma_f32_32x32x16_bf16 v[66:81], v[146:149], v[110:113], v[66:81]
	ds_read2_b64 v[146:149], v185 offset0:228 offset1:230
	s_cbranch_vccnz .LBB0_628
	s_nop 10
	v_max_f32_e32 v0, v66, v66
	v_max_f32_e32 v0, 0xff61b1e6, v0
	v_max3_f32 v0, v0, v67, v68
	v_max3_f32 v0, v0, v69, v70
	v_max3_f32 v0, v0, v71, v72
	v_max3_f32 v0, v0, v73, v74
	v_max3_f32 v0, v0, v75, v76
	v_max3_f32 v0, v0, v77, v78
	v_max3_f32 v0, v0, v79, v80
	s_mov_b64 s[38:39], 0
